# forgetting-attention step-B head: c-tile and K-fragment LDS reads issued before the 16 first-half exps (10 scaled scores renamed to free registers)
# baseline (speedup 1.0000x reference)
.LBB0_1175:
	s_waitcnt vmcnt(5) lgkmcnt(0)
	s_barrier
	v_mul_f32_e32 v5, 0xbe0293ee, v2
	v_fmamk_f32 v236, v96, 0x3e0293ee, v5
	v_fmamk_f32 v237, v97, 0x3e0293ee, v5
	v_fmamk_f32 v238, v98, 0x3e0293ee, v5
	v_fmamk_f32 v239, v99, 0x3e0293ee, v5
	v_fmamk_f32 v10, v100, 0x3e0293ee, v5
	v_fmamk_f32 v11, v101, 0x3e0293ee, v5
	v_fmamk_f32 v12, v102, 0x3e0293ee, v5
	v_fmamk_f32 v13, v103, 0x3e0293ee, v5
	v_fmamk_f32 v14, v104, 0x3e0293ee, v5
	v_fmamk_f32 v15, v105, 0x3e0293ee, v5
	v_fmamk_f32 v240, v106, 0x3e0293ee, v5
	v_fmamk_f32 v241, v107, 0x3e0293ee, v5
	v_fmamk_f32 v242, v108, 0x3e0293ee, v5
	v_fmamk_f32 v243, v109, 0x3e0293ee, v5
	v_fmamk_f32 v244, v110, 0x3e0293ee, v5
	v_fmamk_f32 v245, v111, 0x3e0293ee, v5
	v_fmamk_f32 v112, v80, 0x3e0293ee, v5
	v_fmamk_f32 v113, v81, 0x3e0293ee, v5
	v_fmamk_f32 v114, v82, 0x3e0293ee, v5
	v_fmamk_f32 v115, v83, 0x3e0293ee, v5
	v_fmamk_f32 v116, v84, 0x3e0293ee, v5
	v_fmamk_f32 v117, v85, 0x3e0293ee, v5
	v_fmamk_f32 v118, v86, 0x3e0293ee, v5
	v_fmamk_f32 v119, v87, 0x3e0293ee, v5
	v_fmamk_f32 v120, v88, 0x3e0293ee, v5
	v_fmamk_f32 v121, v89, 0x3e0293ee, v5
	v_fmamk_f32 v122, v90, 0x3e0293ee, v5
	v_fmamk_f32 v123, v91, 0x3e0293ee, v5
	v_fmamk_f32 v124, v92, 0x3e0293ee, v5
	v_fmamk_f32 v125, v93, 0x3e0293ee, v5
	v_fmamk_f32 v126, v94, 0x3e0293ee, v5
	v_fmac_f32_e32 v5, 0x3e0293ee, v95
	s_ashr_i32 s8, s68, 8
	v_lshl_add_u32 v6, s8, 2, v128
	ds_read_b128 v[96:99], v6
	ds_read_b128 v[100:103], v6 offset:32
	ds_read_b128 v[80:83], v6 offset:128
	ds_read_b128 v[84:87], v6 offset:160
	ds_read_b128 v[104:107], v6 offset:64
	ds_read_b128 v[108:111], v6 offset:96
	ds_read_b128 v[88:91], v6 offset:192
	ds_read_b128 v[92:95], v6 offset:224
	s_add_i32 s8, s68, 0
	v_add3_u32 v140, s8, v197, v196
	v_add3_u32 v141, s8, v198, v196
	v_add3_u32 v142, s8, v199, v196
	v_add3_u32 v143, s8, v200, v196
	s_setprio 1
	ds_read_b128 v[6:9], v140 offset:49152
	ds_read_b128 v[220:223], v140 offset:57344
	ds_read_b128 v[224:227], v141 offset:49152
	ds_read_b128 v[228:231], v141 offset:57344
	ds_read_b128 v[232:235], v142 offset:49152
	v_exp_f32_e32 v127, v236
	v_exp_f32_e32 v131, v237
	v_exp_f32_e32 v132, v238
	v_exp_f32_e32 v133, v239
	v_exp_f32_e32 v10, v10
	v_exp_f32_e32 v11, v11
	v_exp_f32_e32 v12, v12
	v_exp_f32_e32 v13, v13
	v_exp_f32_e32 v14, v14
	v_exp_f32_e32 v15, v15
	v_exp_f32_e32 v134, v240
	v_exp_f32_e32 v135, v241
	v_exp_f32_e32 v136, v242
	v_exp_f32_e32 v137, v243
	v_exp_f32_e32 v138, v244
	v_exp_f32_e32 v139, v245
	s_waitcnt lgkmcnt(4)
	v_mfma_f32_32x32x16_bf16 v[96:111], v[6:9], v[172:175], v[96:111]
	ds_read_b128 v[6:9], v142 offset:57344
	s_waitcnt lgkmcnt(4)
	v_mfma_f32_32x32x16_bf16 v[80:95], v[220:223], v[172:175], v[80:95]
	ds_read_b128 v[220:223], v143 offset:49152
	s_add_i32 s8, s61, s90
	s_mov_b32 s9, m0
	s_mov_b32 m0, s8
	s_nop 0
	global_load_lds_dwordx4 v183, s[62:63]
	s_mov_b32 m0, s9
	s_waitcnt lgkmcnt(4)
	v_mfma_f32_32x32x16_bf16 v[96:111], v[224:227], v[168:171], v[96:111]
	ds_read_b128 v[224:227], v143 offset:57344
	s_waitcnt lgkmcnt(4)
	v_mfma_f32_32x32x16_bf16 v[80:95], v[228:231], v[168:171], v[80:95]
	ds_read_b128 v[228:231], v140 offset:49280
	s_waitcnt lgkmcnt(4)
	v_mfma_f32_32x32x16_bf16 v[96:111], v[232:235], v[164:167], v[96:111]
	ds_read_b128 v[232:235], v140 offset:57472
	s_addk_i32 s8, 0x400
	s_mov_b32 s9, m0
	s_mov_b32 m0, s8
	s_nop 0
	global_load_lds_dwordx4 v184, s[62:63]
	s_mov_b32 m0, s9
	s_waitcnt lgkmcnt(4)
	v_mfma_f32_32x32x16_bf16 v[80:95], v[6:9], v[164:167], v[80:95]
	ds_read_b128 v[6:9], v141 offset:49280
	s_waitcnt lgkmcnt(4)
	v_mfma_f32_32x32x16_bf16 v[96:111], v[220:223], v[160:163], v[96:111]
	ds_read_b128 v[220:223], v141 offset:57472
	s_waitcnt lgkmcnt(4)
	v_mfma_f32_32x32x16_bf16 v[80:95], v[224:227], v[160:163], v[80:95]
	ds_read_b128 v[224:227], v142 offset:49280
	s_ashr_i32 s8, s61, 6
	s_cmp_lg_u32 0, -1
	s_cselect_b32 s9, 0, 0
	s_add_i32 s8, s9, s8
	s_add_i32 s8, s8, 0x18800
	s_mov_b32 s9, m0
	s_mov_b32 m0, s8
	s_nop 0
	global_load_lds_dword v185, s[0:1]
	s_mov_b32 m0, s9
	s_waitcnt lgkmcnt(4)
	v_mfma_f32_32x32x16_bf16 v[96:111], v[228:231], v[156:159], v[96:111]
	ds_read_b128 v[228:231], v142 offset:57472
	s_waitcnt lgkmcnt(4)
	v_mfma_f32_32x32x16_bf16 v[80:95], v[232:235], v[156:159], v[80:95]
	ds_read_b128 v[232:235], v143 offset:49280
	s_waitcnt lgkmcnt(4)
	v_mfma_f32_32x32x16_bf16 v[96:111], v[6:9], v[152:155], v[96:111]
	ds_read_b128 v[6:9], v143 offset:57472
	s_add_u32 s8, s56, s66
	s_addc_u32 s9, s57, s67
	s_add_i32 s65, s53, s83
	s_mov_b32 s66, m0
	s_mov_b32 m0, s65
	s_nop 0
	global_load_lds_dwordx4 v187, s[8:9]
	s_mov_b32 m0, s66
	s_waitcnt lgkmcnt(4)
	v_mfma_f32_32x32x16_bf16 v[80:95], v[220:223], v[152:155], v[80:95]
	s_waitcnt lgkmcnt(3)
	v_mfma_f32_32x32x16_bf16 v[96:111], v[224:227], v[148:151], v[96:111]
	s_waitcnt lgkmcnt(2)
	v_mfma_f32_32x32x16_bf16 v[80:95], v[228:231], v[148:151], v[80:95]
	s_addk_i32 s65, 0x400
	s_mov_b32 s66, m0
	s_mov_b32 m0, s65
	s_nop 0
	global_load_lds_dwordx4 v186, s[8:9]
	s_mov_b32 m0, s66
	s_waitcnt lgkmcnt(1)
	v_mfma_f32_32x32x16_bf16 v[96:111], v[232:235], v[144:147], v[96:111]
	s_waitcnt lgkmcnt(0)
	v_mfma_f32_32x32x16_bf16 v[80:95], v[6:9], v[144:147], v[80:95]
	s_setprio 0
	v_exp_f32_e32 v7, v112
	v_exp_f32_e32 v112, v113
	v_exp_f32_e32 v113, v114
	v_exp_f32_e32 v114, v115
	v_exp_f32_e32 v115, v116
	v_exp_f32_e32 v116, v117
	v_exp_f32_e32 v117, v118
	v_exp_f32_e32 v118, v119
	v_exp_f32_e32 v119, v120
	v_exp_f32_e32 v120, v121
	v_exp_f32_e32 v121, v122
	v_exp_f32_e32 v122, v123
	v_exp_f32_e32 v123, v124
	v_exp_f32_e32 v124, v125
	v_exp_f32_e32 v125, v126
	v_exp_f32_e32 v126, v5
	v_add_f32_e32 v5, 0, v127
	v_add_f32_e32 v5, v131, v5
	v_add_f32_e32 v5, v132, v5
	v_add_f32_e32 v5, v133, v5
	v_add_f32_e32 v5, v10, v5
	v_add_f32_e32 v5, v11, v5
	v_add_f32_e32 v5, v12, v5
	v_add_f32_e32 v5, v13, v5
	v_add_f32_e32 v5, v14, v5
	v_add_f32_e32 v5, v15, v5
	v_add_f32_e32 v5, v134, v5
	v_add_f32_e32 v5, v135, v5
	v_add_f32_e32 v5, v136, v5
	v_add_f32_e32 v5, v137, v5
	v_add_f32_e32 v5, v138, v5
	v_add_f32_e32 v5, v139, v5
	v_add_f32_e32 v5, v7, v5
	v_add_f32_e32 v5, v112, v5
	v_add_f32_e32 v5, v113, v5
	v_add_f32_e32 v5, v114, v5
	v_add_f32_e32 v5, v115, v5
	v_add_f32_e32 v5, v116, v5
	v_add_f32_e32 v5, v117, v5
	v_add_f32_e32 v5, v118, v5
	v_add_f32_e32 v5, v119, v5
	v_add_f32_e32 v5, v120, v5
	v_add_f32_e32 v5, v121, v5
	v_add_f32_e32 v5, v122, v5
	v_add_f32_e32 v5, v123, v5
	v_add_f32_e32 v5, v124, v5
	v_add_f32_e32 v5, v125, v5
	v_add_f32_e32 v5, v126, v5
	v_mov_b32_e32 v6, v5
	s_nop 1
	v_permlane32_swap_b32_e32 v5, v6
	v_cvt_pk_bf16_f32 v8, v127, v131
	v_cvt_pk_bf16_f32 v9, v132, v133
	v_cvt_pk_bf16_f32 v10, v10, v11
	v_cvt_pk_bf16_f32 v11, v12, v13
	v_cvt_pk_bf16_f32 v12, v14, v15
	v_cvt_pk_bf16_f32 v13, v134, v135
	v_cvt_pk_bf16_f32 v14, v136, v137
	v_cvt_pk_bf16_f32 v15, v138, v139
	v_cvt_pk_bf16_f32 v112, v7, v112
	v_cvt_pk_bf16_f32 v113, v113, v114
	v_cvt_pk_bf16_f32 v114, v115, v116
	v_cvt_pk_bf16_f32 v115, v117, v118
	v_cvt_pk_bf16_f32 v116, v119, v120
	v_cvt_pk_bf16_f32 v117, v121, v122
	v_cvt_pk_bf16_f32 v118, v123, v124
	v_cvt_pk_bf16_f32 v119, v125, v126
	s_nop 0
	v_add_u32_e32 v7, s61, v193
	ds_read_b64_tr_b16 v[120:121], v7 offset:0
	ds_read_b64_tr_b16 v[122:123], v7 offset:0x800
	ds_read_b64_tr_b16 v[124:125], v7 offset:0x1000
	ds_read_b64_tr_b16 v[126:127], v7 offset:0x1800
	ds_read_b64_tr_b16 v[132:133], v7 offset:0x2000
	ds_read_b64_tr_b16 v[134:135], v7 offset:0x2800
	ds_read_b64_tr_b16 v[136:137], v7 offset:0x3000
	ds_read_b64_tr_b16 v[138:139], v7 offset:0x3800
	s_waitcnt lgkmcnt(6)
	s_nop 0
	v_mfma_f32_32x32x16_bf16 v[16:31], v[8:11], v[120:123], v[16:31]
	ds_read_b64_tr_b16 v[120:121], v7 offset:0x200
	ds_read_b64_tr_b16 v[122:123], v7 offset:0xa00
	s_waitcnt lgkmcnt(6)
	v_mfma_f32_32x32x16_bf16 v[16:31], v[12:15], v[124:127], v[16:31]
	ds_read_b64_tr_b16 v[124:125], v7 offset:0x1200
	ds_read_b64_tr_b16 v[126:127], v7 offset:0x1a00
	s_waitcnt lgkmcnt(6)
	v_mfma_f32_32x32x16_bf16 v[16:31], v[112:115], v[132:135], v[16:31]
	ds_read_b64_tr_b16 v[132:133], v7 offset:0x2200
	ds_read_b64_tr_b16 v[134:135], v7 offset:0x2a00
	s_waitcnt lgkmcnt(6)
	v_mfma_f32_32x32x16_bf16 v[16:31], v[116:119], v[136:139], v[16:31]
	ds_read_b64_tr_b16 v[136:137], v7 offset:0x3200
	ds_read_b64_tr_b16 v[138:139], v7 offset:0x3a00
	s_waitcnt lgkmcnt(6)
	v_mfma_f32_32x32x16_bf16 v[48:63], v[8:11], v[120:123], v[48:63]
	ds_read_b64_tr_b16 v[120:121], v7 offset:0x400
	ds_read_b64_tr_b16 v[122:123], v7 offset:0xc00
	s_waitcnt lgkmcnt(6)
	v_mfma_f32_32x32x16_bf16 v[48:63], v[12:15], v[124:127], v[48:63]
	ds_read_b64_tr_b16 v[124:125], v7 offset:0x1400
	ds_read_b64_tr_b16 v[126:127], v7 offset:0x1c00
	s_waitcnt lgkmcnt(6)
	v_mfma_f32_32x32x16_bf16 v[48:63], v[112:115], v[132:135], v[48:63]
	ds_read_b64_tr_b16 v[132:133], v7 offset:0x2400
	ds_read_b64_tr_b16 v[134:135], v7 offset:0x2c00
	s_waitcnt lgkmcnt(6)
	v_mfma_f32_32x32x16_bf16 v[48:63], v[116:119], v[136:139], v[48:63]
	ds_read_b64_tr_b16 v[136:137], v7 offset:0x3400
	ds_read_b64_tr_b16 v[138:139], v7 offset:0x3c00
	s_waitcnt lgkmcnt(6)
	v_mfma_f32_32x32x16_bf16 v[64:79], v[8:11], v[120:123], v[64:79]
	ds_read_b64_tr_b16 v[120:121], v7 offset:0x600
	ds_read_b64_tr_b16 v[122:123], v7 offset:0xe00
	s_waitcnt lgkmcnt(6)
	v_mfma_f32_32x32x16_bf16 v[64:79], v[12:15], v[124:127], v[64:79]
	ds_read_b64_tr_b16 v[124:125], v7 offset:0x1600
	ds_read_b64_tr_b16 v[126:127], v7 offset:0x1e00
	s_waitcnt lgkmcnt(6)
	v_mfma_f32_32x32x16_bf16 v[64:79], v[112:115], v[132:135], v[64:79]
	ds_read_b64_tr_b16 v[132:133], v7 offset:0x2600
	ds_read_b64_tr_b16 v[134:135], v7 offset:0x2e00
	s_waitcnt lgkmcnt(6)
	v_mfma_f32_32x32x16_bf16 v[64:79], v[116:119], v[136:139], v[64:79]
	ds_read_b64_tr_b16 v[136:137], v7 offset:0x3600
	ds_read_b64_tr_b16 v[138:139], v7 offset:0x3e00
	s_waitcnt lgkmcnt(6)
	v_mfma_f32_32x32x16_bf16 v[32:47], v[8:11], v[120:123], v[32:47]
	s_cmp_le_i32 s91, s69
	s_waitcnt lgkmcnt(4)
	v_mfma_f32_32x32x16_bf16 v[32:47], v[12:15], v[124:127], v[32:47]
	s_waitcnt lgkmcnt(2)
	v_mfma_f32_32x32x16_bf16 v[32:47], v[112:115], v[132:135], v[32:47]
	s_waitcnt lgkmcnt(0)
	v_mfma_f32_32x32x16_bf16 v[32:47], v[116:119], v[136:139], v[32:47]
	s_cbranch_scc1 .LBB0_1177
	v_add_u32_e32 v7, 0x4000007b, v130
	v_cmp_gt_u32_e32 vcc, 2.0, v7
	v_add_u32_e32 v7, 0x5b, v130
	s_nop 0
	v_cndmask_b32_e32 v96, v179, v96, vcc
	v_cmp_lt_u32_e32 vcc, s96, v7
	v_add_u32_e32 v7, 0x7a, v130
	s_nop 0
	v_cndmask_b32_e32 v80, v179, v80, vcc
	v_cmp_lt_u32_e32 vcc, s96, v7
	v_add_u32_e32 v7, 0x5a, v130
	s_nop 0
	v_cndmask_b32_e32 v97, v179, v97, vcc
	v_cmp_lt_u32_e32 vcc, s96, v7
	v_add_u32_e32 v7, 0x79, v130
	s_nop 0
	v_cndmask_b32_e32 v81, v179, v81, vcc
	v_cmp_lt_u32_e32 vcc, s96, v7
	v_add_u32_e32 v7, 0x59, v130
	s_nop 0
	v_cndmask_b32_e32 v98, v179, v98, vcc
	v_cmp_lt_u32_e32 vcc, s96, v7
	v_add_u32_e32 v7, 0x78, v130
	s_nop 0
	v_cndmask_b32_e32 v82, v179, v82, vcc
	v_cmp_lt_u32_e32 vcc, s96, v7
	v_add_u32_e32 v7, 0x58, v130
	s_nop 0
	v_cndmask_b32_e32 v99, v179, v99, vcc
	v_cmp_lt_u32_e32 vcc, s96, v7
	v_add_u32_e32 v7, 0x73, v130
	s_nop 0
	v_cndmask_b32_e32 v83, v179, v83, vcc
	v_cmp_lt_u32_e32 vcc, s96, v7
	v_add_u32_e32 v7, 0x53, v130
	s_nop 0
	v_cndmask_b32_e32 v100, v179, v100, vcc
	v_cmp_lt_u32_e32 vcc, s96, v7
	v_add_u32_e32 v7, 0x72, v130
	s_nop 0
	v_cndmask_b32_e32 v84, v179, v84, vcc
	v_cmp_lt_u32_e32 vcc, s96, v7
	v_add_u32_e32 v7, 0x52, v130
	s_nop 0
	v_cndmask_b32_e32 v101, v179, v101, vcc
	v_cmp_lt_u32_e32 vcc, s96, v7
	v_add_u32_e32 v7, 0x71, v130
	s_nop 0
	v_cndmask_b32_e32 v85, v179, v85, vcc
	v_cmp_lt_u32_e32 vcc, s96, v7
	v_add_u32_e32 v7, 0x51, v130
	s_nop 0
	v_cndmask_b32_e32 v102, v179, v102, vcc
	v_cmp_lt_u32_e32 vcc, s96, v7
	v_add_u32_e32 v7, 0x70, v130
	s_nop 0
	v_cndmask_b32_e32 v86, v179, v86, vcc
	v_cmp_lt_u32_e32 vcc, s96, v7
	v_add_u32_e32 v7, 0x50, v130
	s_nop 0
	v_cndmask_b32_e32 v103, v179, v103, vcc
	v_cmp_lt_u32_e32 vcc, s96, v7
	v_add_u32_e32 v7, 0x6b, v130
	s_nop 0
	v_cndmask_b32_e32 v87, v179, v87, vcc
	v_cmp_lt_u32_e32 vcc, s96, v7
	v_add_u32_e32 v7, 0x4b, v130
	s_nop 0
	v_cndmask_b32_e32 v104, v179, v104, vcc
	v_cmp_lt_u32_e32 vcc, s96, v7
	v_add_u32_e32 v7, 0x6a, v130
	s_nop 0
	v_cndmask_b32_e32 v88, v179, v88, vcc
	v_cmp_lt_u32_e32 vcc, s96, v7
	v_add_u32_e32 v7, 0x4a, v130
	s_nop 0
	v_cndmask_b32_e32 v105, v179, v105, vcc
	v_cmp_lt_u32_e32 vcc, s96, v7
	v_add_u32_e32 v7, 0x69, v130
	s_nop 0
	v_cndmask_b32_e32 v89, v179, v89, vcc
	v_cmp_lt_u32_e32 vcc, s96, v7
	v_add_u32_e32 v7, 0x49, v130
	s_nop 0
	v_cndmask_b32_e32 v106, v179, v106, vcc
	v_cmp_lt_u32_e32 vcc, s96, v7
	v_add_u32_e32 v7, 0x68, v130
	s_nop 0
	v_cndmask_b32_e32 v90, v179, v90, vcc
	v_cmp_lt_u32_e32 vcc, s96, v7
	v_add_u32_e32 v7, 0x48, v130
	s_nop 0
	v_cndmask_b32_e32 v107, v179, v107, vcc
	v_cmp_lt_u32_e32 vcc, s96, v7
	v_add_u32_e32 v7, 0x63, v130
	s_nop 0
	v_cndmask_b32_e32 v91, v179, v91, vcc
	v_cmp_lt_u32_e32 vcc, s96, v7
	v_add_u32_e32 v7, 0x43, v130
	s_nop 0
	v_cndmask_b32_e32 v108, v179, v108, vcc
	v_cmp_lt_u32_e32 vcc, s96, v7
	v_add_u32_e32 v7, 0x62, v130
	s_nop 0
	v_cndmask_b32_e32 v92, v179, v92, vcc
	v_cmp_lt_u32_e32 vcc, s96, v7
	v_add_u32_e32 v7, 0x42, v130
	s_nop 0
	v_cndmask_b32_e32 v109, v179, v109, vcc
	v_cmp_lt_u32_e32 vcc, s96, v7
	v_add_u32_e32 v7, 0x61, v130
	s_nop 0
	v_cndmask_b32_e32 v93, v179, v93, vcc
	v_cmp_lt_u32_e32 vcc, s96, v7
	v_add_u32_e32 v7, 0x41, v130
	s_nop 0
	v_cndmask_b32_e32 v110, v179, v110, vcc
	v_cmp_lt_u32_e32 vcc, s96, v7
	v_add_u32_e32 v7, 0x60, v130
	s_nop 0
	v_cndmask_b32_e32 v94, v179, v94, vcc
	v_cmp_lt_u32_e32 vcc, s96, v7
	v_add_u32_e32 v7, 64, v130
	s_nop 0
	v_cndmask_b32_e32 v111, v179, v111, vcc
	v_cmp_lt_u32_e32 vcc, s96, v7
	s_nop 1
	v_cndmask_b32_e32 v95, v179, v95, vcc
